# MLA attention loop: first-half PV MFMAs issued after exps 0-7 and interleaved with exps 8-15 (softmax VALU overlapped with PV matrix ops), second-half V reads issued as S registers free up
# speedup vs baseline: 1.0056x; 1.0056x over previous
; __device__ __forceinline__ unsigned cvt_pk_bf16(float lo, float hi) { unsigned r; asm volatile("v_cvt_pk_bf16_f32 %0, %1, %2" : "=v"(r) : "v"(lo), "v"(hi)); return r; }
; __device__ __forceinline__ float fast_exp2(float x) { return __builtin_amdgcn_exp2f(x); }
; template <int DQ, int TYPE>
; __device__ __forceinline__ void attn_item(PP p, int layer, int b, int h, int qt, char* lds, const int tid_, unsigned* next_ctr, volatile XLAS unsigned* slot) {
;     ...
;             float ls = 0.f;
; #pragma unroll
;             for (int i = 0; i < 16; ++i) { sacc[i] = fast_exp2(__builtin_fmaf(sacc[i], c, -mnew)); ls += sacc[i]; }
;             l_run = l_run * alpha + ls;
;             if (__builtin_amdgcn_ballot_w64(mx > m_old_) != 0) {
; #pragma unroll
;                 for (int md = 0; md < 4; ++md) O[md] *= alpha;
;             }
; #pragma unroll
;             for (int s2 = 0; s2 < 2; ++s2) {
;                 if (s2 == 0) {
; #pragma unroll
;                     for (int md = 0; md < 4; ++md) { vf[1][md][0] = *(const u32x2*)(vb0 + 16 + md * 32 * VLD); vf[1][md][1] = *(const u32x2*)(vb0 + 16 + md * 32 * VLD + 8); }
;                 }
;                 u32x4 pb;
;                 pb.x = cvt_pk_bf16(sacc[8 * s2 + 0], sacc[8 * s2 + 1]); pb.y = cvt_pk_bf16(sacc[8 * s2 + 2], sacc[8 * s2 + 3]);
;                 pb.z = cvt_pk_bf16(sacc[8 * s2 + 4], sacc[8 * s2 + 5]); pb.w = cvt_pk_bf16(sacc[8 * s2 + 6], sacc[8 * s2 + 7]);
;                 const bf16x8 bfrag = __builtin_bit_cast(bf16x8, pb);
;                 __builtin_amdgcn_sched_barrier(0);
; #pragma unroll
;                 for (int md = 0; md < 4; ++md) {
;                     u32x4 av; av.x = vf[s2][md][0].x; av.y = vf[s2][md][0].y; av.z = vf[s2][md][1].x; av.w = vf[s2][md][1].y;
;                     O[md] = __builtin_amdgcn_mfma_f32_32x32x16_bf16(__builtin_bit_cast(bf16x8, av), bfrag, O[md], 0, 0, 0);
;                 }
;                 __builtin_amdgcn_sched_barrier(0);
;             }
.LBB0_669:
	v_fma_f32 v249, v66, s86, -v200
	v_exp_f32_e32 v205, v249
	v_fma_f32 v249, v67, s86, -v200
	v_exp_f32_e32 v206, v249
	v_fma_f32 v249, v68, s86, -v200
	v_exp_f32_e32 v207, v249
	v_fma_f32 v249, v69, s86, -v200
	v_exp_f32_e32 v208, v249
	v_fma_f32 v249, v70, s86, -v200
	v_add_f32_e32 v248, 0, v205
	v_exp_f32_e32 v209, v249
	v_fma_f32 v249, v71, s86, -v200
	v_add_f32_e32 v248, v206, v248
	v_exp_f32_e32 v210, v249
	v_fma_f32 v249, v72, s86, -v200
	v_add_f32_e32 v248, v207, v248
	v_exp_f32_e32 v211, v249
	v_fma_f32 v249, v73, s86, -v200
	v_add_f32_e32 v248, v208, v248
	v_exp_f32_e32 v212, v249
	ds_read2_b64 v[66:69], v203 offset0:132 offset1:134
	ds_read2_b64 v[70:73], v201 offset0:164 offset1:166
	v_cvt_pk_bf16_f32 v244, v205, v206
	v_cvt_pk_bf16_f32 v245, v207, v208
	v_cvt_pk_bf16_f32 v246, v209, v210
	v_cvt_pk_bf16_f32 v247, v211, v212
	s_waitcnt lgkmcnt(2)
	s_nop 0
	v_mfma_f32_32x32x16_bf16 v[18:33], v[162:165], v[244:247], v[18:33]
	v_fma_f32 v249, v74, s86, -v200
	v_add_f32_e32 v248, v209, v248
	v_exp_f32_e32 v213, v249
	v_fma_f32 v249, v75, s86, -v200
	v_add_f32_e32 v248, v210, v248
	v_exp_f32_e32 v214, v249
	v_mfma_f32_32x32x16_bf16 v[2:17], v[158:161], v[244:247], v[2:17]
	v_fma_f32 v249, v76, s86, -v200
	v_add_f32_e32 v248, v211, v248
	v_exp_f32_e32 v215, v249
	v_fma_f32 v249, v77, s86, -v200
	v_add_f32_e32 v248, v212, v248
	v_exp_f32_e32 v216, v249
	v_mfma_f32_32x32x16_bf16 v[50:65], v[154:157], v[244:247], v[50:65]
	ds_read2_b64 v[74:77], v204 offset0:196 offset1:198
	v_fma_f32 v249, v78, s86, -v200
	v_add_f32_e32 v248, v213, v248
	v_exp_f32_e32 v217, v249
	v_fma_f32 v249, v79, s86, -v200
	v_add_f32_e32 v248, v214, v248
	v_exp_f32_e32 v218, v249
	v_mfma_f32_32x32x16_bf16 v[34:49], v[150:153], v[244:247], v[34:49]
	v_fma_f32 v249, v80, s86, -v200
	v_add_f32_e32 v248, v215, v248
	v_exp_f32_e32 v219, v249
	v_fma_f32 v249, v81, s86, -v200
	v_add_f32_e32 v248, v216, v248
	v_exp_f32_e32 v230, v249
	ds_read2_b64 v[78:81], v202 offset0:228 offset1:230
	v_add_f32_e32 v248, v217, v248
	v_add_f32_e32 v248, v218, v248
	v_add_f32_e32 v248, v219, v248
	v_add_f32_e32 v231, v230, v248
	v_fmac_f32_e32 v231, v199, v192
	v_cvt_pk_bf16_f32 v150, v213, v214
	v_cvt_pk_bf16_f32 v151, v215, v216
	v_cvt_pk_bf16_f32 v152, v217, v218
	v_cvt_pk_bf16_f32 v153, v219, v230
	s_waitcnt lgkmcnt(3)
	v_mfma_f32_32x32x16_bf16 v[18:33], v[66:69], v[150:153], v[18:33]
	s_waitcnt lgkmcnt(2)
	v_mfma_f32_32x32x16_bf16 v[2:17], v[70:73], v[150:153], v[2:17]
	s_waitcnt lgkmcnt(1)
	v_mfma_f32_32x32x16_bf16 v[50:65], v[74:77], v[150:153], v[50:65]
	s_waitcnt lgkmcnt(0)
	v_mfma_f32_32x32x16_bf16 v[34:49], v[78:81], v[150:153], v[34:49]
	v_mov_b32_e32 v199, v231
	s_andn2_b64 vcc, exec, s[12:13]
	s_cbranch_vccz .LBB0_671
	s_branch .LBB0_672
